# ph14: static s_setprio 1 for the wave in HW slot 1 during NA attention
# baseline (speedup 1.0000x reference)
.Lna14_order_done:
	s_getreg_b32 s97, hwreg(HW_REG_HW_ID, 0, 4)
	s_bitcmp1_b32 s97, 0
	s_cbranch_scc0 .Lna14_noprio
	s_setprio 1

.LBB0_1803:
	s_setprio 0
	s_cmp_lt_i32 s23, 16
	s_cbranch_scc1 .LBB0_1856
	s_waitcnt vmcnt(0)
	v_cmp_eq_u32_e32 vcc, 0, v73
	s_waitcnt vmcnt(0)
	v_mov_b32_e32 v2, v146
	v_mov_b32_e32 v4, v148
	s_waitcnt lgkmcnt(0)
	s_barrier
	s_and_saveexec_b64 s[4:5], vcc
	s_cbranch_execz .LBB0_1853
	v_cmp_eq_u32_e32 vcc, 0, v148
	v_mov_b32_e32 v2, v146
	v_mov_b32_e32 v4, v148
	s_waitcnt vmcnt(0) expcnt(0) lgkmcnt(0)
	s_and_saveexec_b64 s[6:7], vcc
	s_cbranch_execz .LBB0_1820
	s_load_dwordx2 s[12:13], s[0:1], 0x468
	s_load_dword s3, s[0:1], 0x470
	s_add_u32 s8, s20, 0x1000
	s_addc_u32 s9, s21, 0
	s_add_u32 s10, s20, 0x1100
	s_waitcnt lgkmcnt(0)
	s_mul_i32 s11, s13, s12
	s_mul_i32 s3, s11, s3
	s_addc_u32 s11, s21, 0
	s_add_u32 s12, s20, 0x1200
	s_addc_u32 s13, s21, 0
	s_add_u32 s14, s20, 0x1300
	s_addc_u32 s15, s21, 0
	s_mov_b32 s26, 1
	v_mov_b32_e32 v18, 0
	s_branch .LBB0_1808
